# step26: sc1 nt (write-through, drop from L2) instead of nt on the two 545MB bf16 intermediate store streams, on top of step20
# speedup vs baseline: 1.0026x; 1.0026x over previous
.LBB0_492:
	s_add_i32 s20, s31, 4
	s_min_u32 s45, s20, 31
	s_lshl_b32 s20, s45, 6
	v_lshl_add_u64 v[150:151], v[186:187], 0, s[20:21]
	global_load_dwordx4 v[166:169], v[150:151], off
	global_load_dwordx4 v[158:161], v[150:151], off offset:2048
	v_lshl_add_u64 v[150:151], v[188:189], 0, s[20:21]
	v_lshl_add_u64 v[154:155], v[190:191], 0, s[20:21]
	global_load_dwordx4 v[162:165], v[150:151], off
	s_nop 0
	global_load_dwordx4 v[150:153], v[154:155], off
	s_nop 0
	global_load_dwordx4 v[154:157], v[154:155], off offset:2048
	s_add_i32 s31, s31, 2
	v_lshl_or_b32 v246, s30, 15, v196
	v_add3_u32 v250, v246, v198, v199
	v_add3_u32 v251, v246, v200, v199
	ds_read_b128 v[230:233], v250 offset:16384
	ds_read_b128 v[234:237], v250 offset:17408
	ds_read_b128 v[238:241], v250 offset:18432
	ds_read_b128 v[242:245], v250 offset:19456
	ds_read_b128 v[246:249], v251
	s_waitcnt lgkmcnt(0)
	v_mfma_f32_16x16x32_bf16 v[146:149], v[230:233], v[246:249], v[146:149]
	v_mfma_f32_16x16x32_bf16 v[142:145], v[234:237], v[246:249], v[142:145]
	v_mfma_f32_16x16x32_bf16 v[138:141], v[238:241], v[246:249], v[138:141]
	v_mfma_f32_16x16x32_bf16 v[134:137], v[242:245], v[246:249], v[134:137]
	ds_read_b128 v[246:249], v251 offset:1024
	s_waitcnt lgkmcnt(0)
	v_mfma_f32_16x16x32_bf16 v[130:133], v[230:233], v[246:249], v[130:133]
	v_mfma_f32_16x16x32_bf16 v[126:129], v[234:237], v[246:249], v[126:129]
	v_mfma_f32_16x16x32_bf16 v[122:125], v[238:241], v[246:249], v[122:125]
	v_mfma_f32_16x16x32_bf16 v[118:121], v[242:245], v[246:249], v[118:121]
	ds_read_b128 v[246:249], v251 offset:2048
	s_waitcnt lgkmcnt(0)
	v_mfma_f32_16x16x32_bf16 v[114:117], v[230:233], v[246:249], v[114:117]
	v_mfma_f32_16x16x32_bf16 v[110:113], v[234:237], v[246:249], v[110:113]
	v_mfma_f32_16x16x32_bf16 v[106:109], v[238:241], v[246:249], v[106:109]
	v_mfma_f32_16x16x32_bf16 v[102:105], v[242:245], v[246:249], v[102:105]
	ds_read_b128 v[246:249], v251 offset:3072
	s_waitcnt lgkmcnt(0)
	v_mfma_f32_16x16x32_bf16 v[98:101], v[230:233], v[246:249], v[98:101]
	v_mfma_f32_16x16x32_bf16 v[94:97], v[234:237], v[246:249], v[94:97]
	v_mfma_f32_16x16x32_bf16 v[90:93], v[238:241], v[246:249], v[90:93]
	v_mfma_f32_16x16x32_bf16 v[82:85], v[242:245], v[246:249], v[82:85]
	ds_read_b128 v[230:233], v170
	ds_read_b128 v[234:237], v170 offset:16
	s_waitcnt vmcnt(9)
	v_lshlrev_b32_e32 v238, 16, v14
	v_and_b32_e32 v239, 0xffff0000, v14
	v_lshlrev_b32_e32 v240, 16, v15
	v_and_b32_e32 v241, 0xffff0000, v15
	s_waitcnt vmcnt(7)
	v_lshlrev_b32_e32 v14, 16, v18
	v_and_b32_e32 v15, 0xffff0000, v18
	v_sub_f32_e32 v14, v14, v238
	v_sub_f32_e32 v15, v15, v239
	v_lshlrev_b32_e32 v242, 16, v16
	v_and_b32_e32 v243, 0xffff0000, v16
	v_lshlrev_b32_e32 v244, 16, v17
	v_and_b32_e32 v245, 0xffff0000, v17
	v_lshlrev_b32_e32 v16, 16, v19
	v_and_b32_e32 v17, 0xffff0000, v19
	s_waitcnt lgkmcnt(1)
	v_fma_f32 v14, v14, v230, v238
	v_fma_f32 v15, v15, v231, v239
	v_cvt_pk_bf16_f32 v14, v14, v15
	v_sub_f32_e32 v15, v16, v240
	v_sub_f32_e32 v16, v17, v241
	v_lshlrev_b32_e32 v18, 16, v20
	v_and_b32_e32 v19, 0xffff0000, v20
	v_fma_f32 v15, v15, v232, v240
	v_fma_f32 v16, v16, v233, v241
	v_cvt_pk_bf16_f32 v15, v15, v16
	v_sub_f32_e32 v16, v18, v242
	v_sub_f32_e32 v17, v19, v243
	v_lshlrev_b32_e32 v20, 16, v21
	v_and_b32_e32 v21, 0xffff0000, v21
	s_waitcnt lgkmcnt(0)
	v_fma_f32 v16, v16, v234, v242
	v_fma_f32 v17, v17, v235, v243
	v_cvt_pk_bf16_f32 v16, v16, v17
	v_sub_f32_e32 v17, v20, v244
	v_sub_f32_e32 v18, v21, v245
	s_lshl_b32 s30, s7, 15
	v_fma_f32 v17, v17, v236, v244
	v_fma_f32 v18, v18, v237, v245
	v_cvt_pk_bf16_f32 v17, v17, v18
	v_or_b32_e32 v18, s30, v193
	ds_write_b128 v18, v[14:17]
	v_lshlrev_b32_e32 v14, 16, v10
	v_and_b32_e32 v10, 0xffff0000, v10
	v_sub_f32_e32 v19, v238, v14
	v_fmac_f32_e32 v14, v19, v230
	v_sub_f32_e32 v19, v239, v10
	v_lshlrev_b32_e32 v15, 16, v11
	v_fmac_f32_e32 v10, v19, v231
	v_and_b32_e32 v11, 0xffff0000, v11
	v_cvt_pk_bf16_f32 v10, v14, v10
	v_sub_f32_e32 v14, v240, v15
	v_lshlrev_b32_e32 v16, 16, v12
	v_fmac_f32_e32 v15, v14, v232
	v_sub_f32_e32 v14, v241, v11
	v_and_b32_e32 v12, 0xffff0000, v12
	v_fmac_f32_e32 v11, v14, v233
	v_sub_f32_e32 v14, v242, v16
	v_lshlrev_b32_e32 v17, 16, v13
	v_fmac_f32_e32 v16, v14, v234
	v_sub_f32_e32 v14, v243, v12
	v_and_b32_e32 v13, 0xffff0000, v13
	v_fmac_f32_e32 v12, v14, v235
	v_sub_f32_e32 v14, v244, v17
	v_fmac_f32_e32 v17, v14, v236
	v_sub_f32_e32 v14, v245, v13
	v_fmac_f32_e32 v13, v14, v237
	v_cvt_pk_bf16_f32 v11, v15, v11
	v_cvt_pk_bf16_f32 v12, v16, v12
	v_cvt_pk_bf16_f32 v13, v17, v13
	v_add_u32_e32 v14, s30, v194
	ds_write_b128 v14, v[10:13]
	s_waitcnt vmcnt(6)
	ds_write_b128 v18, v[2:5] offset:16384
	s_waitcnt vmcnt(5)
	ds_write_b128 v14, v[6:9] offset:16384
	ds_read_b128 v[2:5], v250 offset:16384
	ds_read_b128 v[6:9], v250 offset:17408
	ds_read_b128 v[10:13], v251 offset:4096
	ds_read_b128 v[14:17], v251 offset:5120
	ds_read_b128 v[230:233], v250 offset:18432
	ds_read_b128 v[234:237], v250 offset:19456
	s_min_u32 s20, s31, 28
	s_waitcnt lgkmcnt(3)
	v_mfma_f32_16x16x32_bf16 v[86:89], v[2:5], v[10:13], v[86:89]
	s_lshl_b32 s20, s20, 6
	v_mfma_f32_16x16x32_bf16 v[78:81], v[6:9], v[10:13], v[78:81]
	s_waitcnt lgkmcnt(1)
	v_mfma_f32_16x16x32_bf16 v[74:77], v[230:233], v[10:13], v[74:77]
	s_waitcnt lgkmcnt(0)
	v_mfma_f32_16x16x32_bf16 v[70:73], v[234:237], v[10:13], v[70:73]
	ds_read_b128 v[10:13], v251 offset:6144
	ds_read_b128 v[238:241], v251 offset:7168
	s_waitcnt lgkmcnt(0)
	s_barrier
	v_mfma_f32_16x16x32_bf16 v[66:69], v[2:5], v[14:17], v[66:69]
	v_mfma_f32_16x16x32_bf16 v[46:49], v[2:5], v[10:13], v[46:49]
	v_mfma_f32_16x16x32_bf16 v[30:33], v[2:5], v[238:241], v[30:33]
	v_lshl_add_u64 v[2:3], v[186:187], 0, s[20:21]
	v_mfma_f32_16x16x32_bf16 v[62:65], v[6:9], v[14:17], v[62:65]
	v_mfma_f32_16x16x32_bf16 v[54:57], v[230:233], v[14:17], v[54:57]
	v_mfma_f32_16x16x32_bf16 v[50:53], v[234:237], v[14:17], v[50:53]
	v_mfma_f32_16x16x32_bf16 v[42:45], v[6:9], v[10:13], v[42:45]
	v_mfma_f32_16x16x32_bf16 v[38:41], v[230:233], v[10:13], v[38:41]
	v_mfma_f32_16x16x32_bf16 v[34:37], v[234:237], v[10:13], v[34:37]
	global_load_dwordx4 v[14:17], v[2:3], off offset:192
	global_load_dwordx4 v[10:13], v[2:3], off offset:2240
	v_lshl_add_u64 v[2:3], v[188:189], 0, s[20:21]
	global_load_dwordx4 v[18:21], v[2:3], off offset:192
	v_mfma_f32_16x16x32_bf16 v[26:29], v[6:9], v[238:241], v[26:29]
	v_lshl_add_u64 v[6:7], v[190:191], 0, s[20:21]
	global_load_dwordx4 v[2:5], v[6:7], off offset:192
	s_nop 0
	global_load_dwordx4 v[6:9], v[6:7], off offset:2240
	s_add_i32 s20, s7, 1
	v_mfma_f32_16x16x32_bf16 v[22:25], v[230:233], v[238:241], v[22:25]
	v_mfma_f32_16x16x32_bf16 v[58:61], v[234:237], v[238:241], v[58:61]
	v_or_b32_e32 v246, s30, v196
	v_add3_u32 v250, v246, v198, v199
	v_add3_u32 v251, v246, v200, v199
	ds_read_b128 v[230:233], v250 offset:16384
	ds_read_b128 v[234:237], v250 offset:17408
	ds_read_b128 v[238:241], v250 offset:18432
	ds_read_b128 v[242:245], v250 offset:19456
	ds_read_b128 v[246:249], v251
	s_cmp_lg_u32 s7, 2
	s_cselect_b32 s30, s20, 0
	s_waitcnt lgkmcnt(0)
	v_mfma_f32_16x16x32_bf16 v[146:149], v[230:233], v[246:249], v[146:149]
	v_mfma_f32_16x16x32_bf16 v[142:145], v[234:237], v[246:249], v[142:145]
	v_mfma_f32_16x16x32_bf16 v[138:141], v[238:241], v[246:249], v[138:141]
	v_mfma_f32_16x16x32_bf16 v[134:137], v[242:245], v[246:249], v[134:137]
	ds_read_b128 v[246:249], v251 offset:1024
	s_waitcnt lgkmcnt(0)
	v_mfma_f32_16x16x32_bf16 v[130:133], v[230:233], v[246:249], v[130:133]
	v_mfma_f32_16x16x32_bf16 v[126:129], v[234:237], v[246:249], v[126:129]
	v_mfma_f32_16x16x32_bf16 v[122:125], v[238:241], v[246:249], v[122:125]
	v_mfma_f32_16x16x32_bf16 v[118:121], v[242:245], v[246:249], v[118:121]
	ds_read_b128 v[246:249], v251 offset:2048
	s_waitcnt lgkmcnt(0)
	v_mfma_f32_16x16x32_bf16 v[114:117], v[230:233], v[246:249], v[114:117]
	v_mfma_f32_16x16x32_bf16 v[110:113], v[234:237], v[246:249], v[110:113]
	v_mfma_f32_16x16x32_bf16 v[106:109], v[238:241], v[246:249], v[106:109]
	v_mfma_f32_16x16x32_bf16 v[102:105], v[242:245], v[246:249], v[102:105]
	ds_read_b128 v[246:249], v251 offset:3072
	s_waitcnt lgkmcnt(0)
	v_mfma_f32_16x16x32_bf16 v[98:101], v[230:233], v[246:249], v[98:101]
	v_mfma_f32_16x16x32_bf16 v[94:97], v[234:237], v[246:249], v[94:97]
	v_mfma_f32_16x16x32_bf16 v[90:93], v[238:241], v[246:249], v[90:93]
	v_mfma_f32_16x16x32_bf16 v[82:85], v[242:245], v[246:249], v[82:85]
	v_lshl_add_u32 v234, s45, 7, v197
	ds_read_b128 v[230:233], v234
	ds_read_b128 v[234:237], v234 offset:16
	s_waitcnt vmcnt(9)
	v_lshlrev_b32_e32 v238, 16, v166
	v_and_b32_e32 v166, 0xffff0000, v166
	s_waitcnt vmcnt(7)
	v_lshlrev_b32_e32 v242, 16, v162
	v_and_b32_e32 v162, 0xffff0000, v162
	v_sub_f32_e32 v242, v242, v238
	v_sub_f32_e32 v162, v162, v166
	v_lshlrev_b32_e32 v239, 16, v167
	v_and_b32_e32 v167, 0xffff0000, v167
	v_lshlrev_b32_e32 v243, 16, v163
	v_and_b32_e32 v163, 0xffff0000, v163
	s_waitcnt lgkmcnt(1)
	v_fma_f32 v242, v242, v230, v238
	v_fma_f32 v162, v162, v231, v166
	v_cvt_pk_bf16_f32 v162, v242, v162
	v_sub_f32_e32 v242, v243, v239
	v_sub_f32_e32 v163, v163, v167
	v_lshlrev_b32_e32 v240, 16, v168
	v_and_b32_e32 v168, 0xffff0000, v168
	v_lshlrev_b32_e32 v244, 16, v164
	v_and_b32_e32 v164, 0xffff0000, v164
	v_fma_f32 v242, v242, v232, v239
	v_fma_f32 v163, v163, v233, v167
	v_cvt_pk_bf16_f32 v163, v242, v163
	v_sub_f32_e32 v242, v244, v240
	v_sub_f32_e32 v164, v164, v168
	v_lshlrev_b32_e32 v241, 16, v169
	v_and_b32_e32 v169, 0xffff0000, v169
	v_lshlrev_b32_e32 v245, 16, v165
	v_and_b32_e32 v165, 0xffff0000, v165
	s_waitcnt lgkmcnt(0)
	v_fma_f32 v242, v242, v234, v240
	v_fma_f32 v164, v164, v235, v168
	v_cvt_pk_bf16_f32 v164, v242, v164
	v_sub_f32_e32 v242, v245, v241
	v_sub_f32_e32 v165, v165, v169
	s_lshl_b32 s7, s30, 15
	v_fma_f32 v242, v242, v236, v241
	v_fma_f32 v165, v165, v237, v169
	v_cvt_pk_bf16_f32 v165, v242, v165
	v_or_b32_e32 v242, s7, v193
	ds_write_b128 v242, v[162:165]
	v_lshlrev_b32_e32 v162, 16, v158
	v_and_b32_e32 v158, 0xffff0000, v158
	v_sub_f32_e32 v238, v238, v162
	v_sub_f32_e32 v166, v166, v158
	v_lshlrev_b32_e32 v163, 16, v159
	v_fmac_f32_e32 v162, v238, v230
	v_fmac_f32_e32 v158, v166, v231
	v_and_b32_e32 v159, 0xffff0000, v159
	v_cvt_pk_bf16_f32 v158, v162, v158
	v_sub_f32_e32 v162, v239, v163
	v_lshlrev_b32_e32 v164, 16, v160
	v_fmac_f32_e32 v163, v162, v232
	v_sub_f32_e32 v162, v167, v159
	v_and_b32_e32 v160, 0xffff0000, v160
	v_fmac_f32_e32 v159, v162, v233
	v_sub_f32_e32 v162, v240, v164
	v_lshlrev_b32_e32 v165, 16, v161
	v_fmac_f32_e32 v164, v162, v234
	v_sub_f32_e32 v162, v168, v160
	v_and_b32_e32 v161, 0xffff0000, v161
	v_fmac_f32_e32 v160, v162, v235
	v_sub_f32_e32 v162, v241, v165
	v_fmac_f32_e32 v165, v162, v236
	v_sub_f32_e32 v162, v169, v161
	v_fmac_f32_e32 v161, v162, v237
	v_cvt_pk_bf16_f32 v159, v163, v159
	v_cvt_pk_bf16_f32 v160, v164, v160
	v_cvt_pk_bf16_f32 v161, v165, v161
	v_add_u32_e32 v162, s7, v194
	ds_write_b128 v162, v[158:161]
	s_waitcnt vmcnt(6)
	ds_write_b128 v242, v[150:153] offset:16384
	s_waitcnt vmcnt(5)
	ds_write_b128 v162, v[154:157] offset:16384
	ds_read_b128 v[150:153], v250 offset:16384
	ds_read_b128 v[154:157], v250 offset:17408
	ds_read_b128 v[158:161], v251 offset:4096
	ds_read_b128 v[162:165], v251 offset:5120
	ds_read_b128 v[166:169], v250 offset:18432
	ds_read_b128 v[230:233], v250 offset:19456
	s_add_i32 s7, s30, 1
	s_waitcnt lgkmcnt(3)
	v_mfma_f32_16x16x32_bf16 v[86:89], v[150:153], v[158:161], v[86:89]
	s_cmp_lg_u32 s30, 2
	s_cselect_b32 s7, s7, 0
	v_add_u32_e32 v170, 0x100, v170
	v_mfma_f32_16x16x32_bf16 v[78:81], v[154:157], v[158:161], v[78:81]
	s_cmp_lt_u32 s31, 30
	s_waitcnt lgkmcnt(1)
	v_mfma_f32_16x16x32_bf16 v[74:77], v[166:169], v[158:161], v[74:77]
	s_waitcnt lgkmcnt(0)
	v_mfma_f32_16x16x32_bf16 v[70:73], v[230:233], v[158:161], v[70:73]
	v_mfma_f32_16x16x32_bf16 v[66:69], v[150:153], v[162:165], v[66:69]
	v_mfma_f32_16x16x32_bf16 v[62:65], v[154:157], v[162:165], v[62:65]
	v_mfma_f32_16x16x32_bf16 v[54:57], v[166:169], v[162:165], v[54:57]
	v_mfma_f32_16x16x32_bf16 v[50:53], v[230:233], v[162:165], v[50:53]
	ds_read_b128 v[158:161], v251 offset:6144
	ds_read_b128 v[162:165], v251 offset:7168
	s_waitcnt lgkmcnt(0)
	s_barrier
	v_mfma_f32_16x16x32_bf16 v[46:49], v[150:153], v[158:161], v[46:49]
	v_mfma_f32_16x16x32_bf16 v[42:45], v[154:157], v[158:161], v[42:45]
	v_mfma_f32_16x16x32_bf16 v[38:41], v[166:169], v[158:161], v[38:41]
	v_mfma_f32_16x16x32_bf16 v[34:37], v[230:233], v[158:161], v[34:37]
	v_mfma_f32_16x16x32_bf16 v[30:33], v[150:153], v[162:165], v[30:33]
	v_mfma_f32_16x16x32_bf16 v[26:29], v[154:157], v[162:165], v[26:29]
	v_mfma_f32_16x16x32_bf16 v[22:25], v[166:169], v[162:165], v[22:25]
	v_mfma_f32_16x16x32_bf16 v[58:61], v[230:233], v[162:165], v[58:61]
	s_cbranch_scc1 .LBB0_492
	s_waitcnt vmcnt(1)
	v_cvt_pk_bf16_f32 v2, v146, v147
	v_cvt_pk_bf16_f32 v3, v148, v149
	v_cvt_pk_bf16_f32 v4, v142, v143
	v_cvt_pk_bf16_f32 v5, v144, v145
	ds_write2_b64 v201, v[2:3], v[4:5] offset1:4
	v_cvt_pk_bf16_f32 v2, v138, v139
	v_cvt_pk_bf16_f32 v3, v140, v141
	v_cvt_pk_bf16_f32 v4, v134, v135
	v_cvt_pk_bf16_f32 v5, v136, v137
	ds_write2_b64 v201, v[2:3], v[4:5] offset0:8 offset1:12
	v_cvt_pk_bf16_f32 v2, v130, v131
	v_cvt_pk_bf16_f32 v3, v132, v133
	v_cvt_pk_bf16_f32 v4, v126, v127
	v_cvt_pk_bf16_f32 v5, v128, v129
	s_waitcnt vmcnt(0)
	v_add_u32_e32 v6, 0x2000, v201
	ds_write2_b64 v6, v[2:3], v[4:5] offset0:32 offset1:36
	v_cvt_pk_bf16_f32 v2, v122, v123
	v_cvt_pk_bf16_f32 v3, v124, v125
	v_cvt_pk_bf16_f32 v4, v118, v119
	v_cvt_pk_bf16_f32 v5, v120, v121
	ds_write2_b64 v6, v[2:3], v[4:5] offset0:40 offset1:44
	v_cvt_pk_bf16_f32 v2, v114, v115
	v_cvt_pk_bf16_f32 v3, v116, v117
	v_cvt_pk_bf16_f32 v4, v110, v111
	v_cvt_pk_bf16_f32 v5, v112, v113
	v_add_u32_e32 v6, 0x4000, v201
	ds_write2_b64 v6, v[2:3], v[4:5] offset0:64 offset1:68
	v_cvt_pk_bf16_f32 v2, v106, v107
	v_cvt_pk_bf16_f32 v3, v108, v109
	v_cvt_pk_bf16_f32 v4, v102, v103
	v_cvt_pk_bf16_f32 v5, v104, v105
	ds_write2_b64 v6, v[2:3], v[4:5] offset0:72 offset1:76
	v_cvt_pk_bf16_f32 v2, v98, v99
	v_cvt_pk_bf16_f32 v3, v100, v101
	v_cvt_pk_bf16_f32 v4, v94, v95
	v_cvt_pk_bf16_f32 v5, v96, v97
	v_add_u32_e32 v6, 0x6000, v201
	ds_write2_b64 v6, v[2:3], v[4:5] offset0:96 offset1:100
	v_cvt_pk_bf16_f32 v2, v90, v91
	v_cvt_pk_bf16_f32 v3, v92, v93
	v_cvt_pk_bf16_f32 v4, v82, v83
	v_cvt_pk_bf16_f32 v5, v84, v85
	ds_write2_b64 v6, v[2:3], v[4:5] offset0:104 offset1:108
	v_cvt_pk_bf16_f32 v2, v86, v87
	v_cvt_pk_bf16_f32 v3, v88, v89
	v_cvt_pk_bf16_f32 v4, v78, v79
	v_cvt_pk_bf16_f32 v5, v80, v81
	v_add_u32_e32 v6, 0x8000, v201
	ds_write2_b64 v6, v[2:3], v[4:5] offset0:128 offset1:132
	v_cvt_pk_bf16_f32 v2, v74, v75
	v_cvt_pk_bf16_f32 v3, v76, v77
	v_cvt_pk_bf16_f32 v4, v70, v71
	v_cvt_pk_bf16_f32 v5, v72, v73
	ds_write2_b64 v6, v[2:3], v[4:5] offset0:136 offset1:140
	v_cvt_pk_bf16_f32 v2, v66, v67
	v_cvt_pk_bf16_f32 v3, v68, v69
	v_cvt_pk_bf16_f32 v4, v62, v63
	v_cvt_pk_bf16_f32 v5, v64, v65
	v_add_u32_e32 v6, 0xa000, v201
	ds_write2_b64 v6, v[2:3], v[4:5] offset0:160 offset1:164
	v_cvt_pk_bf16_f32 v2, v54, v55
	v_cvt_pk_bf16_f32 v3, v56, v57
	v_cvt_pk_bf16_f32 v4, v50, v51
	v_cvt_pk_bf16_f32 v5, v52, v53
	ds_write2_b64 v6, v[2:3], v[4:5] offset0:168 offset1:172
	v_cvt_pk_bf16_f32 v2, v46, v47
	v_cvt_pk_bf16_f32 v3, v48, v49
	v_cvt_pk_bf16_f32 v4, v42, v43
	v_cvt_pk_bf16_f32 v5, v44, v45
	v_add_u32_e32 v6, 0xc000, v201
	ds_write2_b64 v6, v[2:3], v[4:5] offset0:192 offset1:196
	v_cvt_pk_bf16_f32 v2, v38, v39
	v_cvt_pk_bf16_f32 v3, v40, v41
	v_cvt_pk_bf16_f32 v4, v34, v35
	v_cvt_pk_bf16_f32 v5, v36, v37
	ds_write2_b64 v6, v[2:3], v[4:5] offset0:200 offset1:204
	v_cvt_pk_bf16_f32 v2, v30, v31
	v_cvt_pk_bf16_f32 v3, v32, v33
	v_cvt_pk_bf16_f32 v4, v26, v27
	v_cvt_pk_bf16_f32 v5, v28, v29
	v_add_u32_e32 v6, 0xe000, v201
	ds_write2_b64 v6, v[2:3], v[4:5] offset0:224 offset1:228
	v_cvt_pk_bf16_f32 v2, v22, v23
	v_cvt_pk_bf16_f32 v3, v24, v25
	v_cvt_pk_bf16_f32 v4, v58, v59
	v_cvt_pk_bf16_f32 v5, v60, v61
	ds_write2_b64 v6, v[2:3], v[4:5] offset0:232 offset1:236
	s_waitcnt lgkmcnt(0)
	s_barrier
	ds_read_b128 v[2:5], v218
	s_sub_i32 s6, s6, s44
	v_or_b32_e32 v6, s26, v202
	s_ashr_i32 s7, s6, 31
	v_ashrrev_i32_e32 v7, 31, v6
	v_lshl_add_u64 v[14:15], s[6:7], 1, v[182:183]
	v_lshlrev_b64 v[6:7], 12, v[6:7]
	v_lshl_add_u64 v[10:11], v[14:15], 0, v[6:7]
	ds_read_b128 v[6:9], v218 offset:16896
	s_waitcnt lgkmcnt(1)
	global_store_dwordx4 v[10:11], v[2:5], off sc1 nt
	ds_read_b128 v[2:5], v219
	v_or_b32_e32 v10, s26, v203
	v_ashrrev_i32_e32 v11, 31, v10
	v_lshlrev_b64 v[10:11], 12, v[10:11]
	v_lshl_add_u64 v[16:17], v[14:15], 0, v[10:11]
	ds_read_b128 v[10:13], v220
	s_waitcnt lgkmcnt(1)
	global_store_dwordx4 v[16:17], v[2:5], off sc1 nt
	s_nop 1
	v_or_b32_e32 v2, 32, v202
	v_or_b32_e32 v2, s26, v2
	v_ashrrev_i32_e32 v3, 31, v2
	v_lshlrev_b64 v[2:3], 12, v[2:3]
	v_lshl_add_u64 v[2:3], v[14:15], 0, v[2:3]
	global_store_dwordx4 v[2:3], v[6:9], off sc1 nt
	v_or_b32_e32 v2, s26, v204
	v_ashrrev_i32_e32 v3, 31, v2
	v_lshlrev_b64 v[2:3], 12, v[2:3]
	v_lshl_add_u64 v[2:3], v[14:15], 0, v[2:3]
	s_waitcnt lgkmcnt(0)
	global_store_dwordx4 v[2:3], v[10:13], off sc1 nt
	ds_read_b128 v[2:5], v218 offset:33792
	v_or_b32_e32 v6, s26, v205
	v_ashrrev_i32_e32 v7, 31, v6
	v_lshlrev_b64 v[6:7], 12, v[6:7]
	v_lshl_add_u64 v[10:11], v[14:15], 0, v[6:7]
	ds_read_b128 v[6:9], v218 offset:50688
	s_waitcnt lgkmcnt(1)
	global_store_dwordx4 v[10:11], v[2:5], off sc1 nt
	ds_read_b128 v[2:5], v221
	v_or_b32_e32 v10, s26, v206
	v_ashrrev_i32_e32 v11, 31, v10
	v_lshlrev_b64 v[10:11], 12, v[10:11]
	v_lshl_add_u64 v[16:17], v[14:15], 0, v[10:11]
	ds_read_b128 v[10:13], v222
	s_waitcnt lgkmcnt(1)
	global_store_dwordx4 v[16:17], v[2:5], off sc1 nt
	s_nop 1
	v_or_b32_e32 v2, s26, v207
	v_ashrrev_i32_e32 v3, 31, v2
	v_lshlrev_b64 v[2:3], 12, v[2:3]
	v_lshl_add_u64 v[2:3], v[14:15], 0, v[2:3]
	global_store_dwordx4 v[2:3], v[6:9], off sc1 nt
	v_or_b32_e32 v2, s26, v208
	v_ashrrev_i32_e32 v3, 31, v2
	v_lshlrev_b64 v[2:3], 12, v[2:3]
	v_lshl_add_u64 v[2:3], v[14:15], 0, v[2:3]
	s_waitcnt lgkmcnt(0)
	global_store_dwordx4 v[2:3], v[10:13], off sc1 nt
	ds_read_b128 v[2:5], v223
	v_or_b32_e32 v6, s26, v209
	v_ashrrev_i32_e32 v7, 31, v6
	v_lshlrev_b64 v[6:7], 12, v[6:7]
	v_lshl_add_u64 v[10:11], v[14:15], 0, v[6:7]
	ds_read_b128 v[6:9], v223 offset:16896
	s_waitcnt lgkmcnt(1)
	global_store_dwordx4 v[10:11], v[2:5], off sc1 nt
	ds_read_b128 v[2:5], v224
	v_or_b32_e32 v10, s26, v210
	v_ashrrev_i32_e32 v11, 31, v10
	v_lshlrev_b64 v[10:11], 12, v[10:11]
	v_lshl_add_u64 v[16:17], v[14:15], 0, v[10:11]
	ds_read_b128 v[10:13], v225
	s_waitcnt lgkmcnt(1)
	global_store_dwordx4 v[16:17], v[2:5], off sc1 nt
	s_nop 1
	v_or_b32_e32 v2, s26, v211
	v_ashrrev_i32_e32 v3, 31, v2
	v_lshlrev_b64 v[2:3], 12, v[2:3]
	v_lshl_add_u64 v[2:3], v[14:15], 0, v[2:3]
	global_store_dwordx4 v[2:3], v[6:9], off sc1 nt
	v_or_b32_e32 v2, s26, v212
	v_ashrrev_i32_e32 v3, 31, v2
	v_lshlrev_b64 v[2:3], 12, v[2:3]
	v_lshl_add_u64 v[2:3], v[14:15], 0, v[2:3]
	s_waitcnt lgkmcnt(0)
	global_store_dwordx4 v[2:3], v[10:13], off sc1 nt
	ds_read_b128 v[2:5], v223 offset:33792
	v_or_b32_e32 v6, s27, v213
	v_ashrrev_i32_e32 v7, 31, v6
	v_lshlrev_b64 v[6:7], 12, v[6:7]
	v_lshl_add_u64 v[10:11], v[14:15], 0, v[6:7]
	ds_read_b128 v[6:9], v223 offset:50688
	s_waitcnt lgkmcnt(1)
	global_store_dwordx4 v[10:11], v[2:5], off sc1 nt
	ds_read_b128 v[2:5], v226
	v_or_b32_e32 v10, s27, v214
	v_ashrrev_i32_e32 v11, 31, v10
	v_lshlrev_b64 v[10:11], 12, v[10:11]
	v_lshl_add_u64 v[16:17], v[14:15], 0, v[10:11]
	ds_read_b128 v[10:13], v227
	s_waitcnt lgkmcnt(1)
	global_store_dwordx4 v[16:17], v[2:5], off sc1 nt
	s_nop 1
	v_or_b32_e32 v2, s27, v215
	v_ashrrev_i32_e32 v3, 31, v2
	v_lshlrev_b64 v[2:3], 12, v[2:3]
	v_lshl_add_u64 v[2:3], v[14:15], 0, v[2:3]
	global_store_dwordx4 v[2:3], v[6:9], off sc1 nt
	v_add_u32_e32 v2, s26, v216
	v_ashrrev_i32_e32 v3, 31, v2
	v_lshlrev_b64 v[2:3], 12, v[2:3]
	v_lshl_add_u64 v[2:3], v[14:15], 0, v[2:3]
	s_waitcnt lgkmcnt(0)
	global_store_dwordx4 v[2:3], v[10:13], off sc1 nt
	s_barrier
	s_barrier
	s_and_saveexec_b64 s[6:7], s[0:1]
	s_cbranch_execz .LBB0_482
	ds_write_b32 v217, v229
	s_branch .LBB0_482

.LBB0_816:
	ds_read_b128 v[138:141], v136
	ds_read_b128 v[142:145], v135
	ds_read_b128 v[218:221], v135 offset:16896
	ds_read_b128 v[222:225], v137
	v_add_u32_e32 v226, s6, v134
	v_add_u32_e32 v228, s6, v133
	v_add_u32_e32 v230, s6, v132
	v_ashrrev_i32_e32 v227, 31, v226
	v_add_u32_e32 v232, 32, v226
	s_add_i32 s6, s6, 64
	v_ashrrev_i32_e32 v229, 31, v228
	v_ashrrev_i32_e32 v231, 31, v230
	v_lshlrev_b64 v[226:227], 12, v[226:227]
	v_ashrrev_i32_e32 v233, 31, v232
	v_add_u32_e32 v137, 0x8400, v137
	v_add_u32_e32 v136, 0x8400, v136
	v_add_u32_e32 v135, 0x8400, v135
	s_cmpk_eq_i32 s6, 0x100
	v_lshlrev_b64 v[228:229], 12, v[228:229]
	v_lshlrev_b64 v[230:231], 12, v[230:231]
	v_lshl_add_u64 v[226:227], v[130:131], 0, v[226:227]
	v_lshlrev_b64 v[232:233], 12, v[232:233]
	v_lshl_add_u64 v[228:229], v[130:131], 0, v[228:229]
	v_lshl_add_u64 v[230:231], v[130:131], 0, v[230:231]
	v_lshl_add_u64 v[232:233], v[130:131], 0, v[232:233]
	s_waitcnt lgkmcnt(2)
	global_store_dwordx4 v[226:227], v[142:145], off sc1 nt
	global_store_dwordx4 v[228:229], v[138:141], off sc1 nt
	s_waitcnt lgkmcnt(1)
	global_store_dwordx4 v[232:233], v[218:221], off sc1 nt
	s_waitcnt lgkmcnt(0)
	global_store_dwordx4 v[230:231], v[222:225], off sc1 nt
	s_cbranch_scc0 .LBB0_816
	s_and_b64 vcc, exec, s[34:35]
	s_barrier
	s_cbranch_vccz .LBB0_955
	v_cndmask_b32_e64 v130, 0, 1, s[38:39]
	v_cmp_ne_u32_e64 s[6:7], 1, v130
	s_nop 1
	s_and_b64 vcc, exec, s[6:7]
	s_cbranch_vccnz .Lp1_nogain
	global_load_dwordx4 v[240:243], v[150:151], off
	global_load_dwordx4 v[244:247], v[150:151], off offset:64
	global_load_dwordx4 v[248:251], v[150:151], off offset:128
	s_waitcnt vmcnt(0)
